# v60 plus SwiGLU epilogue fold: rcp(fma(e,m,m)) with m=ssq/1024+eps held in an initialized register pair (removes 32 packed + 8 scalar VALU per wave per tile)
# baseline (speedup 1.0000x reference)
; __device__ __forceinline__ void rows_rstd(const float* ssq, int row0, int fq, float (&rs)[2][4]) {
;     f32x4 p[2][4];
; #pragma unroll
;     for (int ai = 0; ai < 2; ++ai)
; #pragma unroll
;         for (int m = 0; m < 4; ++m) p[ai][m] = *(const f32x4*)(ssq + (size_t)(row0 + ai * HALF + m * 16) * 16 + 4 * fq);
; #pragma unroll
;     for (int ai = 0; ai < 2; ++ai)
; #pragma unroll
;         for (int m = 0; m < 4; ++m) { float s = (p[ai][m][0] + p[ai][m][1]) + (p[ai][m][2] + p[ai][m][3]); s += __shfl_xor(s, 16); s += __shfl_xor(s, 32); rs[ai][m] = __builtin_amdgcn_rsqf(s * (1.0f / (float)DM) + RMS_EPS); }
; }
;     __device__ __forceinline__ void operator()(const f32x4 (&acc)[2][2][4][2], const Unit& u, int wr, int wc, int fr, int fq) const {
;         const int row0 = u.pm * BM + wr * 64 + fr, col0 = u.pn * HALF + wc * 32 + 8 * fq;
;         float rsv[2][4]; rows_rstd(ssq, row0, fq, rsv);
; #pragma unroll
;         for (int ai = 0; ai < 2; ++ai)
; #pragma unroll
;             for (int m = 0; m < 4; ++m) {
;                 const int row = row0 + ai * HALF + m * 16; const float rs = rsv[ai][m], cexp = -1.4426950408889634f * rs, rs2 = rs * rs;
;                 const f32x4 g0 = acc[ai][0][m][0], g1 = acc[ai][0][m][1], u0 = acc[ai][1][m][0], u1 = acc[ai][1][m][1];
;                 const f32x4 t0 = g0 * cexp, t1 = g1 * cexp;
;                 f32x4 d0 = (f32x4){__builtin_amdgcn_exp2f(t0[0]), __builtin_amdgcn_exp2f(t0[1]), __builtin_amdgcn_exp2f(t0[2]), __builtin_amdgcn_exp2f(t0[3])} + 1.0f;
;                 f32x4 d1 = (f32x4){__builtin_amdgcn_exp2f(t1[0]), __builtin_amdgcn_exp2f(t1[1]), __builtin_amdgcn_exp2f(t1[2]), __builtin_amdgcn_exp2f(t1[3])} + 1.0f;
;                 const f32x4 r0 = (f32x4){__builtin_amdgcn_rcpf(d0[0]), __builtin_amdgcn_rcpf(d0[1]), __builtin_amdgcn_rcpf(d0[2]), __builtin_amdgcn_rcpf(d0[3])} * rs2;
;                 const f32x4 r1 = (f32x4){__builtin_amdgcn_rcpf(d1[0]), __builtin_amdgcn_rcpf(d1[1]), __builtin_amdgcn_rcpf(d1[2]), __builtin_amdgcn_rcpf(d1[3])} * rs2;
;                 const f32x4 a0 = (g0 * u0) * r0, a1 = (g1 * u1) * r1;
;                 u32x4 w; w.x = cvt_pk_bf16(a0[0], a0[1]); w.y = cvt_pk_bf16(a0[2], a0[3]); w.z = cvt_pk_bf16(a1[0], a1[1]); w.w = cvt_pk_bf16(a1[2], a1[3]);
;                 *(u32x4*)(O + (((size_t)(row >> 8) * (DFF / BK) + (col0 >> 6)) * BM + (row & 255)) * BK + (col0 & 63)) = w;
.Lalign2_skip0:
	s_waitcnt vmcnt(0)
	v_mov_b32_e32 v194, v163
	v_mov_b32_e32 v195, v164
	v_mov_b32_e32 v163, v165
	v_pk_add_f32 v[162:163], v[194:195], v[162:163]
	v_mov_b32_e32 v164, v167
	v_mov_b32_e32 v165, v168
	v_mov_b32_e32 v167, v169
	v_add_f32_e32 v151, v162, v163
	v_pk_add_f32 v[162:163], v[164:165], v[166:167]
	v_mov_b32_e32 v168, v171
	v_mov_b32_e32 v169, v172
	v_mov_b32_e32 v171, v173
	v_mov_b32_e32 v172, v175
	v_mov_b32_e32 v173, v176
	v_mov_b32_e32 v175, v177
	v_mov_b32_e32 v176, v179
	v_mov_b32_e32 v177, v180
	v_mov_b32_e32 v179, v181
	v_pk_add_f32 v[164:165], v[168:169], v[170:171]
	v_pk_add_f32 v[166:167], v[172:173], v[174:175]
	ds_bpermute_b32 v153, v136, v151
	v_add_f32_e32 v161, v162, v163
	v_pk_add_f32 v[168:169], v[176:177], v[178:179]
	v_add_f32_e32 v162, v164, v165
	v_add_f32_e32 v163, v166, v167
	ds_bpermute_b32 v166, v136, v161
	v_add_f32_e32 v164, v168, v169
	ds_bpermute_b32 v167, v136, v162
	ds_bpermute_b32 v168, v136, v163
	ds_bpermute_b32 v169, v136, v164
	s_waitcnt lgkmcnt(4)
	v_add_f32_e32 v151, v151, v153
	ds_bpermute_b32 v153, v149, v151
	s_waitcnt lgkmcnt(4)
	v_add_f32_e32 v161, v161, v166
	s_waitcnt lgkmcnt(3)
	v_add_f32_e32 v162, v162, v167
	s_waitcnt lgkmcnt(2)
	v_add_f32_e32 v163, v163, v168
	ds_bpermute_b32 v166, v149, v161
	v_mov_b32_e32 v180, v183
	v_mov_b32_e32 v181, v184
	v_mov_b32_e32 v183, v185
	s_waitcnt lgkmcnt(2)
	v_add_f32_e32 v164, v164, v169
	ds_bpermute_b32 v167, v149, v162
	ds_bpermute_b32 v168, v149, v163
	v_pk_add_f32 v[170:171], v[180:181], v[182:183]
	ds_bpermute_b32 v169, v149, v164
	v_add_f32_e32 v165, v170, v171
	ds_bpermute_b32 v170, v136, v165
	s_waitcnt lgkmcnt(5)
	v_add_f32_e32 v151, v151, v153
	v_fmamk_f32 v232, v151, 0x3a800000, v160
	v_mov_b32_e32 v233, v232
	s_waitcnt lgkmcnt(4)
	v_add_f32_e32 v153, v161, v166
	s_waitcnt lgkmcnt(3)
	v_add_f32_e32 v161, v162, v167
	s_waitcnt lgkmcnt(2)
	v_add_f32_e32 v162, v163, v168
	v_rsq_f32_e32 v166, v232
	v_fmamk_f32 v234, v153, 0x3a800000, v160
	v_mov_b32_e32 v235, v234
	v_fmamk_f32 v238, v161, 0x3a800000, v160
	v_mov_b32_e32 v239, v238
	v_fmamk_f32 v240, v162, 0x3a800000, v160
	v_mov_b32_e32 v241, v240
	v_rsq_f32_e32 v172, v234
	s_waitcnt lgkmcnt(1)
	v_add_f32_e32 v151, v164, v169
	v_mov_b32_e32 v162, v187
	v_mov_b32_e32 v163, v188
	v_mov_b32_e32 v187, v189
	v_fmamk_f32 v236, v151, 0x3a800000, v160
	v_mov_b32_e32 v237, v236
	v_pk_add_f32 v[162:163], v[162:163], v[186:187]
	v_rsq_f32_e32 v173, v236
	s_waitcnt lgkmcnt(0)
	v_add_f32_e32 v151, v165, v170
	v_add_f32_e32 v165, v162, v163
	v_mov_b32_e32 v162, v191
	v_mov_b32_e32 v163, v192
	v_mov_b32_e32 v191, v193
	v_pk_add_f32 v[162:163], v[162:163], v[190:191]
	ds_bpermute_b32 v167, v136, v165
	v_add_f32_e32 v162, v162, v163
	ds_bpermute_b32 v136, v136, v162
	ds_bpermute_b32 v164, v149, v151
	v_rsq_f32_e32 v153, v238
	s_waitcnt lgkmcnt(2)
	v_add_f32_e32 v163, v165, v167
	v_rsq_f32_e32 v161, v240
	s_waitcnt lgkmcnt(1)
	v_add_f32_e32 v136, v162, v136
	s_waitcnt lgkmcnt(0)
	v_add_f32_e32 v151, v151, v164
	ds_bpermute_b32 v164, v149, v163
	ds_bpermute_b32 v149, v149, v136
	v_fmamk_f32 v242, v151, 0x3a800000, v160
	v_mov_b32_e32 v243, v242
	v_rsq_f32_e32 v174, v242
	s_waitcnt lgkmcnt(1)
	v_add_f32_e32 v151, v163, v164
	s_waitcnt lgkmcnt(0)
	v_add_f32_e32 v136, v136, v149
	v_fmamk_f32 v244, v151, 0x3a800000, v160
	v_mov_b32_e32 v245, v244
	v_fmamk_f32 v246, v136, 0x3a800000, v160
	v_mov_b32_e32 v247, v246
	v_rsq_f32_e32 v175, v244
	v_rsq_f32_e32 v151, v246
	v_mul_f32_e32 v136, 0xbfb8aa3b, v166
	v_pk_mul_f32 v[166:167], v[124:125], v[136:137] op_sel_hi:[1,0]
	v_pk_mul_f32 v[164:165], v[126:127], v[136:137] op_sel_hi:[1,0]
	v_pk_mul_f32 v[168:169], v[122:123], v[136:137] op_sel_hi:[1,0]
	v_pk_mul_f32 v[170:171], v[120:121], v[136:137] op_sel_hi:[1,0]
	v_exp_f32_e32 v166, v166
	v_exp_f32_e32 v167, v167
	v_exp_f32_e32 v164, v164
	v_exp_f32_e32 v165, v165
	v_exp_f32_e32 v170, v170
	v_exp_f32_e32 v168, v168
	v_exp_f32_e32 v169, v169
	v_exp_f32_e32 v171, v171
	v_pk_fma_f32 v[166:167], v[166:167], v[232:233], v[232:233]
	v_pk_fma_f32 v[164:165], v[164:165], v[232:233], v[232:233]
	v_pk_fma_f32 v[168:169], v[168:169], v[232:233], v[232:233]
	v_pk_fma_f32 v[170:171], v[170:171], v[232:233], v[232:233]
	v_rcp_f32_e32 v166, v166
	v_rcp_f32_e32 v167, v167
	v_rcp_f32_e32 v164, v164
	v_rcp_f32_e32 v165, v165
	v_rcp_f32_e32 v170, v170
	v_rcp_f32_e32 v171, v171
	v_rcp_f32_e32 v168, v168
	v_rcp_f32_e32 v169, v169
	s_nop 0
	v_pk_mul_f32 v[116:117], v[116:117], v[166:167]
	v_pk_mul_f32 v[120:121], v[114:115], v[168:169]
	v_pk_mul_f32 v[114:115], v[112:113], v[170:171]
	v_cvt_pk_bf16_f32 v112, v116, v117
	v_lshlrev_b32_e32 v116, 7, v152
	v_and_b32_e32 v136, 0x6780, v116
	v_pk_mul_f32 v[118:119], v[118:119], v[164:165]
	v_lshl_add_u64 v[116:117], s[60:61], 0, v[136:137]
	v_mov_b32_e32 v149, v137
	v_cvt_pk_bf16_f32 v113, v118, v119
	v_cvt_pk_bf16_f32 v114, v114, v115
	v_cvt_pk_bf16_f32 v115, v120, v121
	v_lshl_add_u64 v[116:117], v[116:117], 0, v[148:149]
	global_store_dwordx4 v[116:117], v[112:115], off
	s_nop 1
	v_mul_f32_e32 v112, 0xbfb8aa3b, v172
	v_pk_mul_f32 v[118:119], v[110:111], v[112:113] op_sel_hi:[1,0]
	v_pk_mul_f32 v[120:121], v[108:109], v[112:113] op_sel_hi:[1,0]
	v_pk_mul_f32 v[122:123], v[106:107], v[112:113] op_sel_hi:[1,0]
	v_pk_mul_f32 v[112:113], v[104:105], v[112:113] op_sel_hi:[1,0]
	v_exp_f32_e32 v120, v120
	v_exp_f32_e32 v121, v121
	v_exp_f32_e32 v118, v118
	v_exp_f32_e32 v119, v119
	v_exp_f32_e32 v112, v112
	v_exp_f32_e32 v122, v122
	v_exp_f32_e32 v123, v123
	v_exp_f32_e32 v113, v113
	v_pk_fma_f32 v[118:119], v[118:119], v[234:235], v[234:235]
	v_pk_fma_f32 v[120:121], v[120:121], v[234:235], v[234:235]
; __device__ __forceinline__ unsigned cvt_pk_bf16(float lo, float hi) { typedef float f2 __attribute__((ext_vector_type(2))); const bf16v2 r = __builtin_convertvector((f2){lo, hi}, bf16v2); return __builtin_bit_cast(unsigned, r); }
;     __device__ __forceinline__ void operator()(const f32x4 (&acc)[2][2][4][2], const Unit& u, int wr, int wc, int fr, int fq) const {
;     ...
;                 const int row = row0 + ai * HALF + m * 16; const float rs = rsv[ai][m], cexp = -1.4426950408889634f * rs, rs2 = rs * rs;
;                 const f32x4 g0 = acc[ai][0][m][0], g1 = acc[ai][0][m][1], u0 = acc[ai][1][m][0], u1 = acc[ai][1][m][1];
;                 const f32x4 t0 = g0 * cexp, t1 = g1 * cexp;
;                 f32x4 d0 = (f32x4){__builtin_amdgcn_exp2f(t0[0]), __builtin_amdgcn_exp2f(t0[1]), __builtin_amdgcn_exp2f(t0[2]), __builtin_amdgcn_exp2f(t0[3])} + 1.0f;
;                 f32x4 d1 = (f32x4){__builtin_amdgcn_exp2f(t1[0]), __builtin_amdgcn_exp2f(t1[1]), __builtin_amdgcn_exp2f(t1[2]), __builtin_amdgcn_exp2f(t1[3])} + 1.0f;
;                 const f32x4 r0 = (f32x4){__builtin_amdgcn_rcpf(d0[0]), __builtin_amdgcn_rcpf(d0[1]), __builtin_amdgcn_rcpf(d0[2]), __builtin_amdgcn_rcpf(d0[3])} * rs2;
;                 const f32x4 r1 = (f32x4){__builtin_amdgcn_rcpf(d1[0]), __builtin_amdgcn_rcpf(d1[1]), __builtin_amdgcn_rcpf(d1[2]), __builtin_amdgcn_rcpf(d1[3])} * rs2;
;                 const f32x4 a0 = (g0 * u0) * r0, a1 = (g1 * u1) * r1;
;                 u32x4 w; w.x = cvt_pk_bf16(a0[0], a0[1]); w.y = cvt_pk_bf16(a0[2], a0[3]); w.z = cvt_pk_bf16(a1[0], a1[1]); w.w = cvt_pk_bf16(a1[2], a1[3]);
;                 *(u32x4*)(O + (((size_t)(row >> 8) * (DFF / BK) + (col0 >> 6)) * BM + (row & 255)) * BK + (col0 & 63)) = w;
	v_pk_fma_f32 v[122:123], v[122:123], v[234:235], v[234:235]
	v_pk_fma_f32 v[112:113], v[112:113], v[234:235], v[234:235]
	v_rcp_f32_e32 v120, v120
	v_rcp_f32_e32 v121, v121
	v_rcp_f32_e32 v118, v118
	v_rcp_f32_e32 v119, v119
	v_rcp_f32_e32 v112, v112
	v_rcp_f32_e32 v113, v113
	v_rcp_f32_e32 v122, v122
	v_rcp_f32_e32 v123, v123
	s_nop 0
	v_pk_mul_f32 v[102:103], v[102:103], v[118:119]
	v_pk_mul_f32 v[100:101], v[100:101], v[120:121]
	v_pk_mul_f32 v[104:105], v[98:99], v[122:123]
	v_pk_mul_f32 v[98:99], v[96:97], v[112:113]
	v_cvt_pk_bf16_f32 v96, v100, v101
	v_cvt_pk_bf16_f32 v97, v102, v103
	v_cvt_pk_bf16_f32 v98, v98, v99
	v_cvt_pk_bf16_f32 v99, v104, v105
	global_store_dwordx4 v[116:117], v[96:99], off offset:2048
	s_nop 1
	v_mul_f32_e32 v96, 0xbfb8aa3b, v153
	v_pk_mul_f32 v[102:103], v[92:93], v[96:97] op_sel_hi:[1,0]
	v_pk_mul_f32 v[100:101], v[94:95], v[96:97] op_sel_hi:[1,0]
	v_pk_mul_f32 v[104:105], v[90:91], v[96:97] op_sel_hi:[1,0]
	v_pk_mul_f32 v[96:97], v[88:89], v[96:97] op_sel_hi:[1,0]
	v_exp_f32_e32 v102, v102
	v_exp_f32_e32 v103, v103
	v_exp_f32_e32 v100, v100
	v_exp_f32_e32 v101, v101
	v_exp_f32_e32 v96, v96
	v_exp_f32_e32 v104, v104
	v_exp_f32_e32 v105, v105
	v_exp_f32_e32 v97, v97
	v_pk_fma_f32 v[102:103], v[102:103], v[238:239], v[238:239]
	v_pk_fma_f32 v[100:101], v[100:101], v[238:239], v[238:239]
	v_pk_fma_f32 v[104:105], v[104:105], v[238:239], v[238:239]
	v_pk_fma_f32 v[96:97], v[96:97], v[238:239], v[238:239]
	v_rcp_f32_e32 v102, v102
	v_rcp_f32_e32 v103, v103
	v_rcp_f32_e32 v100, v100
	v_rcp_f32_e32 v101, v101
	v_rcp_f32_e32 v96, v96
	v_rcp_f32_e32 v97, v97
	v_rcp_f32_e32 v104, v104
	v_rcp_f32_e32 v105, v105
	s_nop 0
	v_pk_mul_f32 v[84:85], v[84:85], v[102:103]
	v_pk_mul_f32 v[86:87], v[86:87], v[100:101]
	v_pk_mul_f32 v[88:89], v[82:83], v[104:105]
	v_pk_mul_f32 v[82:83], v[80:81], v[96:97]
	v_cvt_pk_bf16_f32 v80, v84, v85
	v_add_co_u32_e32 v84, vcc, s80, v116
	v_cvt_pk_bf16_f32 v81, v86, v87
	v_cvt_pk_bf16_f32 v82, v82, v83
	v_cvt_pk_bf16_f32 v83, v88, v89
	v_addc_co_u32_e32 v85, vcc, 0, v117, vcc
	global_store_dwordx4 v[84:85], v[80:83], off
	s_nop 1
	v_mul_f32_e32 v80, 0xbfb8aa3b, v161
	v_pk_mul_f32 v[86:87], v[78:79], v[80:81] op_sel_hi:[1,0]
	v_pk_mul_f32 v[88:89], v[76:77], v[80:81] op_sel_hi:[1,0]
	v_pk_mul_f32 v[90:91], v[74:75], v[80:81] op_sel_hi:[1,0]
	v_pk_mul_f32 v[80:81], v[72:73], v[80:81] op_sel_hi:[1,0]
	v_exp_f32_e32 v88, v88
	v_exp_f32_e32 v89, v89
	v_exp_f32_e32 v86, v86
	v_exp_f32_e32 v87, v87
	v_exp_f32_e32 v80, v80
	v_exp_f32_e32 v90, v90
	v_exp_f32_e32 v91, v91
	v_exp_f32_e32 v81, v81
	v_pk_fma_f32 v[86:87], v[86:87], v[240:241], v[240:241]
	v_pk_fma_f32 v[88:89], v[88:89], v[240:241], v[240:241]
	v_pk_fma_f32 v[90:91], v[90:91], v[240:241], v[240:241]
	v_pk_fma_f32 v[80:81], v[80:81], v[240:241], v[240:241]
	v_rcp_f32_e32 v88, v88
	v_rcp_f32_e32 v89, v89
	v_rcp_f32_e32 v86, v86
	v_rcp_f32_e32 v87, v87
	v_rcp_f32_e32 v80, v80
	v_rcp_f32_e32 v81, v81
	v_rcp_f32_e32 v90, v90
	v_rcp_f32_e32 v91, v91
	s_nop 0
	v_pk_mul_f32 v[70:71], v[70:71], v[86:87]
	v_pk_mul_f32 v[68:69], v[68:69], v[88:89]
	v_pk_mul_f32 v[72:73], v[66:67], v[90:91]
	v_pk_mul_f32 v[66:67], v[64:65], v[80:81]
	v_cvt_pk_bf16_f32 v64, v68, v69
	v_cvt_pk_bf16_f32 v65, v70, v71
	v_cvt_pk_bf16_f32 v66, v66, v67
	v_cvt_pk_bf16_f32 v67, v72, v73
	global_store_dwordx4 v[84:85], v[64:67], off offset:2048
	s_nop 0
	v_mul_f32_e32 v66, 0xbfb8aa3b, v173
	v_pk_mul_f32 v[70:71], v[62:63], v[66:67] op_sel_hi:[1,0]
	v_pk_mul_f32 v[72:73], v[60:61], v[66:67] op_sel_hi:[1,0]
	v_pk_mul_f32 v[74:75], v[58:59], v[66:67] op_sel_hi:[1,0]
	v_pk_mul_f32 v[66:67], v[56:57], v[66:67] op_sel_hi:[1,0]
	v_exp_f32_e32 v70, v70
	v_exp_f32_e32 v71, v71
	v_exp_f32_e32 v72, v72
	v_exp_f32_e32 v73, v73
	v_exp_f32_e32 v66, v66
	v_exp_f32_e32 v74, v74
	v_exp_f32_e32 v75, v75
	v_exp_f32_e32 v67, v67
	v_pk_fma_f32 v[70:71], v[70:71], v[236:237], v[236:237]
	v_pk_fma_f32 v[72:73], v[72:73], v[236:237], v[236:237]
	v_pk_fma_f32 v[74:75], v[74:75], v[236:237], v[236:237]
	v_pk_fma_f32 v[66:67], v[66:67], v[236:237], v[236:237]
	v_rcp_f32_e32 v70, v70
	v_rcp_f32_e32 v71, v71
	v_rcp_f32_e32 v72, v72
	v_rcp_f32_e32 v73, v73
	v_rcp_f32_e32 v66, v66
	v_rcp_f32_e32 v67, v67
	v_rcp_f32_e32 v74, v74
	v_rcp_f32_e32 v75, v75
	v_lshrrev_b32_e32 v64, 8, v150
	v_mad_i32_i24 v64, v64, 44, s41
	v_ashrrev_i32_e32 v65, 31, v64
	s_nop 0
	v_pk_mul_f32 v[54:55], v[54:55], v[70:71]
	v_lshlrev_b64 v[64:65], 15, v[64:65]
	v_pk_mul_f32 v[52:53], v[52:53], v[72:73]
; #define PG8_BAR __builtin_amdgcn_s_barrier()
;     __device__ __forceinline__ void operator()(const f32x4 (&acc)[2][2][4][2], const Unit& u, int wr, int wc, int fr, int fq) const {
;     ...
;                 const int row = row0 + ai * HALF + m * 16; const float rs = rsv[ai][m], cexp = -1.4426950408889634f * rs, rs2 = rs * rs;
;                 const f32x4 g0 = acc[ai][0][m][0], g1 = acc[ai][0][m][1], u0 = acc[ai][1][m][0], u1 = acc[ai][1][m][1];
;                 const f32x4 t0 = g0 * cexp, t1 = g1 * cexp;
;                 f32x4 d0 = (f32x4){__builtin_amdgcn_exp2f(t0[0]), __builtin_amdgcn_exp2f(t0[1]), __builtin_amdgcn_exp2f(t0[2]), __builtin_amdgcn_exp2f(t0[3])} + 1.0f;
;                 f32x4 d1 = (f32x4){__builtin_amdgcn_exp2f(t1[0]), __builtin_amdgcn_exp2f(t1[1]), __builtin_amdgcn_exp2f(t1[2]), __builtin_amdgcn_exp2f(t1[3])} + 1.0f;
;                 const f32x4 r0 = (f32x4){__builtin_amdgcn_rcpf(d0[0]), __builtin_amdgcn_rcpf(d0[1]), __builtin_amdgcn_rcpf(d0[2]), __builtin_amdgcn_rcpf(d0[3])} * rs2;
;                 const f32x4 r1 = (f32x4){__builtin_amdgcn_rcpf(d1[0]), __builtin_amdgcn_rcpf(d1[1]), __builtin_amdgcn_rcpf(d1[2]), __builtin_amdgcn_rcpf(d1[3])} * rs2;
;                 const f32x4 a0 = (g0 * u0) * r0, a1 = (g1 * u1) * r1;
;                 u32x4 w; w.x = cvt_pk_bf16(a0[0], a0[1]); w.y = cvt_pk_bf16(a0[2], a0[3]); w.z = cvt_pk_bf16(a1[0], a1[1]); w.w = cvt_pk_bf16(a1[2], a1[3]);
;                 *(u32x4*)(O + (((size_t)(row >> 8) * (DFF / BK) + (col0 >> 6)) * BM + (row & 255)) * BK + (col0 & 63)) = w;
; template <class Epi, class Sched, bool ALIGN_EPI = false, bool SP2 = false, bool ATILED = false>
; __device__ __forceinline__ void gemm_phase(PG8_LAS unsigned char* lds, const Gemm g, const Sched& S, const Epi& E) {
;     ...
;         if constexpr (ALIGN_EPI) { if (wr == 0) PG8_BAR; }
;         if constexpr (!Epi::AFTER_DRAIN) { E(acc, cur, wr, wc, fr, fq); S.done(cur); }
;         if (!has_next) break;
; #pragma unroll
;         for (int a = 0; a < 2; ++a)
; #pragma unroll
;             for (int b = 0; b < 2; ++b)
; #pragma unroll
;                 for (int m = 0; m < 4; ++m)
; #pragma unroll
;                     for (int n = 0; n < 2; ++n) acc[a][b][m][n] = (f32x4){0.f, 0.f, 0.f, 0.f};
;         cur = nxt; cA = nA; cB = nB; ++ui;
;         if constexpr (ALIGN_EPI) { if (wr == 1) PG8_BAR; }
	v_pk_mul_f32 v[56:57], v[50:51], v[74:75]
	v_pk_mul_f32 v[50:51], v[48:49], v[66:67]
	v_cvt_pk_bf16_f32 v49, v54, v55
	v_lshlrev_b32_e32 v54, 7, v150
	v_cvt_pk_bf16_f32 v48, v52, v53
	v_lshl_add_u64 v[52:53], s[36:37], 0, v[64:65]
	v_and_b32_e32 v136, 0x6780, v54
	v_lshl_add_u64 v[52:53], v[52:53], 0, v[136:137]
	v_cvt_pk_bf16_f32 v50, v50, v51
	v_cvt_pk_bf16_f32 v51, v56, v57
	v_lshl_add_u64 v[52:53], v[52:53], 0, v[148:149]
	global_store_dwordx4 v[52:53], v[48:51], off
	s_nop 1
	v_mul_f32_e32 v48, 0xbfb8aa3b, v174
	v_pk_mul_f32 v[54:55], v[46:47], v[48:49] op_sel_hi:[1,0]
	v_pk_mul_f32 v[56:57], v[44:45], v[48:49] op_sel_hi:[1,0]
	v_pk_mul_f32 v[58:59], v[42:43], v[48:49] op_sel_hi:[1,0]
	v_pk_mul_f32 v[48:49], v[40:41], v[48:49] op_sel_hi:[1,0]
	v_exp_f32_e32 v56, v56
	v_exp_f32_e32 v57, v57
	v_exp_f32_e32 v54, v54
	v_exp_f32_e32 v55, v55
	v_exp_f32_e32 v48, v48
	v_exp_f32_e32 v58, v58
	v_exp_f32_e32 v59, v59
	v_exp_f32_e32 v49, v49
	v_pk_fma_f32 v[54:55], v[54:55], v[242:243], v[242:243]
	v_pk_fma_f32 v[56:57], v[56:57], v[242:243], v[242:243]
	v_pk_fma_f32 v[58:59], v[58:59], v[242:243], v[242:243]
	v_pk_fma_f32 v[48:49], v[48:49], v[242:243], v[242:243]
	v_rcp_f32_e32 v56, v56
	v_rcp_f32_e32 v57, v57
	v_rcp_f32_e32 v54, v54
	v_rcp_f32_e32 v55, v55
	v_rcp_f32_e32 v48, v48
	v_rcp_f32_e32 v49, v49
	v_rcp_f32_e32 v58, v58
	v_rcp_f32_e32 v59, v59
	s_nop 0
	v_pk_mul_f32 v[38:39], v[38:39], v[54:55]
	v_pk_mul_f32 v[36:37], v[36:37], v[56:57]
	v_pk_mul_f32 v[40:41], v[34:35], v[58:59]
	v_pk_mul_f32 v[34:35], v[32:33], v[48:49]
	v_cvt_pk_bf16_f32 v32, v36, v37
	v_cvt_pk_bf16_f32 v33, v38, v39
	v_cvt_pk_bf16_f32 v34, v34, v35
	v_cvt_pk_bf16_f32 v35, v40, v41
	global_store_dwordx4 v[52:53], v[32:35], off offset:2048
	s_nop 1
	v_mul_f32_e32 v32, 0xbfb8aa3b, v175
	v_pk_mul_f32 v[38:39], v[28:29], v[32:33] op_sel_hi:[1,0]
	v_pk_mul_f32 v[36:37], v[30:31], v[32:33] op_sel_hi:[1,0]
	v_pk_mul_f32 v[40:41], v[26:27], v[32:33] op_sel_hi:[1,0]
	v_pk_mul_f32 v[32:33], v[24:25], v[32:33] op_sel_hi:[1,0]
	v_exp_f32_e32 v38, v38
	v_exp_f32_e32 v39, v39
	v_exp_f32_e32 v36, v36
	v_exp_f32_e32 v37, v37
	v_exp_f32_e32 v32, v32
	v_exp_f32_e32 v40, v40
	v_exp_f32_e32 v41, v41
	v_exp_f32_e32 v33, v33
	v_pk_fma_f32 v[38:39], v[38:39], v[244:245], v[244:245]
	v_pk_fma_f32 v[36:37], v[36:37], v[244:245], v[244:245]
	v_pk_fma_f32 v[40:41], v[40:41], v[244:245], v[244:245]
	v_pk_fma_f32 v[32:33], v[32:33], v[244:245], v[244:245]
	v_rcp_f32_e32 v38, v38
	v_rcp_f32_e32 v39, v39
	v_rcp_f32_e32 v36, v36
	v_rcp_f32_e32 v37, v37
	v_rcp_f32_e32 v32, v32
	v_rcp_f32_e32 v33, v33
	v_rcp_f32_e32 v40, v40
	v_rcp_f32_e32 v41, v41
	s_nop 0
	v_pk_mul_f32 v[20:21], v[20:21], v[38:39]
	v_pk_mul_f32 v[22:23], v[22:23], v[36:37]
	v_pk_mul_f32 v[24:25], v[18:19], v[40:41]
	v_pk_mul_f32 v[18:19], v[16:17], v[32:33]
	v_cvt_pk_bf16_f32 v16, v20, v21
	v_add_co_u32_e32 v20, vcc, s80, v52
	v_cvt_pk_bf16_f32 v17, v22, v23
	v_cvt_pk_bf16_f32 v18, v18, v19
	v_cvt_pk_bf16_f32 v19, v24, v25
	v_addc_co_u32_e32 v21, vcc, 0, v53, vcc
	global_store_dwordx4 v[20:21], v[16:19], off
	s_andn2_b64 vcc, exec, s[0:1]
	s_mov_b64 s[0:1], -1
	v_mul_f32_e32 v16, 0xbfb8aa3b, v151
	v_pk_mul_f32 v[22:23], v[14:15], v[16:17] op_sel_hi:[1,0]
	v_pk_mul_f32 v[24:25], v[12:13], v[16:17] op_sel_hi:[1,0]
	v_pk_mul_f32 v[26:27], v[10:11], v[16:17] op_sel_hi:[1,0]
	v_pk_mul_f32 v[16:17], v[8:9], v[16:17] op_sel_hi:[1,0]
	v_exp_f32_e32 v24, v24
	v_exp_f32_e32 v25, v25
	v_exp_f32_e32 v22, v22
	v_exp_f32_e32 v23, v23
	v_exp_f32_e32 v16, v16
	v_exp_f32_e32 v26, v26
	v_exp_f32_e32 v27, v27
	v_exp_f32_e32 v17, v17
	v_pk_fma_f32 v[22:23], v[22:23], v[246:247], v[246:247]
	v_pk_fma_f32 v[24:25], v[24:25], v[246:247], v[246:247]
	v_pk_fma_f32 v[26:27], v[26:27], v[246:247], v[246:247]
	v_pk_fma_f32 v[16:17], v[16:17], v[246:247], v[246:247]
	v_rcp_f32_e32 v24, v24
	v_rcp_f32_e32 v25, v25
	v_rcp_f32_e32 v22, v22
	v_rcp_f32_e32 v23, v23
	v_rcp_f32_e32 v16, v16
	v_rcp_f32_e32 v17, v17
	v_rcp_f32_e32 v26, v26
	v_rcp_f32_e32 v27, v27
	s_nop 0
	v_pk_mul_f32 v[6:7], v[6:7], v[22:23]
	v_pk_mul_f32 v[4:5], v[4:5], v[24:25]
	v_pk_mul_f32 v[8:9], v[2:3], v[26:27]
	v_pk_mul_f32 v[2:3], v[0:1], v[16:17]
	v_cvt_pk_bf16_f32 v0, v4, v5
	v_cvt_pk_bf16_f32 v1, v6, v7
	v_cvt_pk_bf16_f32 v2, v2, v3
	v_cvt_pk_bf16_f32 v3, v8, v9
	global_store_dwordx4 v[20:21], v[0:3], off offset:2048
	s_cbranch_vccnz .LBB0_129
	s_andn2_b64 vcc, exec, s[4:5]
	s_cbranch_vccnz .LBB0_128
	s_barrier
	s_branch .LBB0_128

; __device__ __forceinline__ void rows_rstd(const float* ssq, int row0, int fq, float (&rs)[2][4]) {
;     f32x4 p[2][4];
; #pragma unroll
;     for (int ai = 0; ai < 2; ++ai)
; #pragma unroll
;         for (int m = 0; m < 4; ++m) p[ai][m] = *(const f32x4*)(ssq + (size_t)(row0 + ai * HALF + m * 16) * 16 + 4 * fq);
; #pragma unroll
;     for (int ai = 0; ai < 2; ++ai)
; #pragma unroll
;         for (int m = 0; m < 4; ++m) { float s = (p[ai][m][0] + p[ai][m][1]) + (p[ai][m][2] + p[ai][m][3]); s += __shfl_xor(s, 16); s += __shfl_xor(s, 32); rs[ai][m] = __builtin_amdgcn_rsqf(s * (1.0f / (float)DM) + RMS_EPS); }
; }
;     __device__ __forceinline__ void operator()(const f32x4 (&acc)[2][2][4][2], const Unit& u, int wr, int wc, int fr, int fq) const {
;         const int row0 = u.pm * BM + wr * 64 + fr, col0 = u.pn * HALF + wc * 32 + 8 * fq;
;         float rsv[2][4]; rows_rstd(ssq, row0, fq, rsv);
; #pragma unroll
;         for (int ai = 0; ai < 2; ++ai)
; #pragma unroll
;             for (int m = 0; m < 4; ++m) {
;                 const int row = row0 + ai * HALF + m * 16; const float rs = rsv[ai][m], cexp = -1.4426950408889634f * rs, rs2 = rs * rs;
;                 const f32x4 g0 = acc[ai][0][m][0], g1 = acc[ai][0][m][1], u0 = acc[ai][1][m][0], u1 = acc[ai][1][m][1];
;                 const f32x4 t0 = g0 * cexp, t1 = g1 * cexp;
;                 f32x4 d0 = (f32x4){__builtin_amdgcn_exp2f(t0[0]), __builtin_amdgcn_exp2f(t0[1]), __builtin_amdgcn_exp2f(t0[2]), __builtin_amdgcn_exp2f(t0[3])} + 1.0f;
;                 f32x4 d1 = (f32x4){__builtin_amdgcn_exp2f(t1[0]), __builtin_amdgcn_exp2f(t1[1]), __builtin_amdgcn_exp2f(t1[2]), __builtin_amdgcn_exp2f(t1[3])} + 1.0f;
;                 const f32x4 r0 = (f32x4){__builtin_amdgcn_rcpf(d0[0]), __builtin_amdgcn_rcpf(d0[1]), __builtin_amdgcn_rcpf(d0[2]), __builtin_amdgcn_rcpf(d0[3])} * rs2;
;                 const f32x4 r1 = (f32x4){__builtin_amdgcn_rcpf(d1[0]), __builtin_amdgcn_rcpf(d1[1]), __builtin_amdgcn_rcpf(d1[2]), __builtin_amdgcn_rcpf(d1[3])} * rs2;
;                 const f32x4 a0 = (g0 * u0) * r0, a1 = (g1 * u1) * r1;
;                 u32x4 w; w.x = cvt_pk_bf16(a0[0], a0[1]); w.y = cvt_pk_bf16(a0[2], a0[3]); w.z = cvt_pk_bf16(a1[0], a1[1]); w.w = cvt_pk_bf16(a1[2], a1[3]);
;                 *(u32x4*)(O + (((size_t)(row >> 8) * (DFF / BK) + (col0 >> 6)) * BM + (row & 255)) * BK + (col0 & 63)) = w;
.Lalign2_skip4:
	s_waitcnt vmcnt(0)
	v_mov_b32_e32 v194, v163
	v_mov_b32_e32 v195, v164
	v_mov_b32_e32 v163, v165
	v_pk_add_f32 v[162:163], v[194:195], v[162:163]
	v_mov_b32_e32 v164, v167
	v_mov_b32_e32 v165, v168
	v_mov_b32_e32 v167, v169
	v_add_f32_e32 v151, v162, v163
	v_pk_add_f32 v[162:163], v[164:165], v[166:167]
	v_mov_b32_e32 v168, v171
	v_mov_b32_e32 v169, v172
	v_mov_b32_e32 v171, v173
	v_mov_b32_e32 v172, v175
	v_mov_b32_e32 v173, v176
	v_mov_b32_e32 v175, v177
	v_mov_b32_e32 v176, v179
	v_mov_b32_e32 v177, v180
	v_mov_b32_e32 v179, v181
	v_pk_add_f32 v[164:165], v[168:169], v[170:171]
	v_pk_add_f32 v[166:167], v[172:173], v[174:175]
	ds_bpermute_b32 v153, v136, v151
	v_add_f32_e32 v161, v162, v163
	v_pk_add_f32 v[168:169], v[176:177], v[178:179]
	v_add_f32_e32 v162, v164, v165
	v_add_f32_e32 v163, v166, v167
	ds_bpermute_b32 v166, v136, v161
	v_add_f32_e32 v164, v168, v169
	ds_bpermute_b32 v167, v136, v162
	ds_bpermute_b32 v168, v136, v163
	ds_bpermute_b32 v169, v136, v164
	s_waitcnt lgkmcnt(4)
	v_add_f32_e32 v151, v151, v153
	ds_bpermute_b32 v153, v149, v151
	s_waitcnt lgkmcnt(4)
	v_add_f32_e32 v161, v161, v166
	s_waitcnt lgkmcnt(3)
	v_add_f32_e32 v162, v162, v167
	s_waitcnt lgkmcnt(2)
	v_add_f32_e32 v163, v163, v168
	ds_bpermute_b32 v166, v149, v161
	v_mov_b32_e32 v180, v183
	v_mov_b32_e32 v181, v184
	v_mov_b32_e32 v183, v185
	s_waitcnt lgkmcnt(2)
	v_add_f32_e32 v164, v164, v169
	ds_bpermute_b32 v167, v149, v162
	ds_bpermute_b32 v168, v149, v163
	v_pk_add_f32 v[170:171], v[180:181], v[182:183]
	ds_bpermute_b32 v169, v149, v164
	v_add_f32_e32 v165, v170, v171
	ds_bpermute_b32 v170, v136, v165
	s_waitcnt lgkmcnt(5)
	v_add_f32_e32 v151, v151, v153
	v_fmamk_f32 v232, v151, 0x3a800000, v160
	v_mov_b32_e32 v233, v232
	s_waitcnt lgkmcnt(4)
	v_add_f32_e32 v153, v161, v166
	s_waitcnt lgkmcnt(3)
	v_add_f32_e32 v161, v162, v167
	s_waitcnt lgkmcnt(2)
	v_add_f32_e32 v162, v163, v168
	v_rsq_f32_e32 v166, v232
	v_fmamk_f32 v234, v153, 0x3a800000, v160
	v_mov_b32_e32 v235, v234
	v_fmamk_f32 v238, v161, 0x3a800000, v160
	v_mov_b32_e32 v239, v238
	v_fmamk_f32 v240, v162, 0x3a800000, v160
	v_mov_b32_e32 v241, v240
	v_rsq_f32_e32 v172, v234
	s_waitcnt lgkmcnt(1)
	v_add_f32_e32 v151, v164, v169
	v_mov_b32_e32 v162, v187
	v_mov_b32_e32 v163, v188
	v_mov_b32_e32 v187, v189
	v_fmamk_f32 v236, v151, 0x3a800000, v160
	v_mov_b32_e32 v237, v236
	v_pk_add_f32 v[162:163], v[162:163], v[186:187]
	v_rsq_f32_e32 v173, v236
	s_waitcnt lgkmcnt(0)
	v_add_f32_e32 v151, v165, v170
	v_add_f32_e32 v165, v162, v163
	v_mov_b32_e32 v162, v191
	v_mov_b32_e32 v163, v192
	v_mov_b32_e32 v191, v193
	v_pk_add_f32 v[162:163], v[162:163], v[190:191]
	ds_bpermute_b32 v167, v136, v165
	v_add_f32_e32 v162, v162, v163
	ds_bpermute_b32 v136, v136, v162
	ds_bpermute_b32 v164, v149, v151
	v_rsq_f32_e32 v153, v238
	s_waitcnt lgkmcnt(2)
	v_add_f32_e32 v163, v165, v167
	v_rsq_f32_e32 v161, v240
	s_waitcnt lgkmcnt(1)
	v_add_f32_e32 v136, v162, v136
	s_waitcnt lgkmcnt(0)
	v_add_f32_e32 v151, v151, v164
	ds_bpermute_b32 v164, v149, v163
	ds_bpermute_b32 v149, v149, v136
	v_fmamk_f32 v242, v151, 0x3a800000, v160
	v_mov_b32_e32 v243, v242
	v_rsq_f32_e32 v174, v242
	s_waitcnt lgkmcnt(1)
	v_add_f32_e32 v151, v163, v164
	s_waitcnt lgkmcnt(0)
	v_add_f32_e32 v136, v136, v149
	v_fmamk_f32 v244, v151, 0x3a800000, v160
	v_mov_b32_e32 v245, v244
	v_fmamk_f32 v246, v136, 0x3a800000, v160
	v_mov_b32_e32 v247, v246
	v_rsq_f32_e32 v175, v244
	v_rsq_f32_e32 v151, v246
	v_mul_f32_e32 v136, 0xbfb8aa3b, v166
	v_pk_mul_f32 v[166:167], v[124:125], v[136:137] op_sel_hi:[1,0]
	v_pk_mul_f32 v[164:165], v[126:127], v[136:137] op_sel_hi:[1,0]
	v_pk_mul_f32 v[168:169], v[122:123], v[136:137] op_sel_hi:[1,0]
	v_pk_mul_f32 v[170:171], v[120:121], v[136:137] op_sel_hi:[1,0]
	v_exp_f32_e32 v166, v166
	v_exp_f32_e32 v167, v167
	v_exp_f32_e32 v164, v164
	v_exp_f32_e32 v165, v165
	v_exp_f32_e32 v170, v170
	v_exp_f32_e32 v168, v168
	v_exp_f32_e32 v169, v169
	v_exp_f32_e32 v171, v171
	v_pk_fma_f32 v[166:167], v[166:167], v[232:233], v[232:233]
	v_pk_fma_f32 v[164:165], v[164:165], v[232:233], v[232:233]
	v_pk_fma_f32 v[168:169], v[168:169], v[232:233], v[232:233]
	v_pk_fma_f32 v[170:171], v[170:171], v[232:233], v[232:233]
	v_rcp_f32_e32 v166, v166
	v_rcp_f32_e32 v167, v167
	v_rcp_f32_e32 v164, v164
	v_rcp_f32_e32 v165, v165
	v_rcp_f32_e32 v170, v170
	v_rcp_f32_e32 v171, v171
	v_rcp_f32_e32 v168, v168
	v_rcp_f32_e32 v169, v169
	s_nop 0
	v_pk_mul_f32 v[116:117], v[116:117], v[166:167]
	v_pk_mul_f32 v[120:121], v[114:115], v[168:169]
	v_pk_mul_f32 v[114:115], v[112:113], v[170:171]
	v_cvt_pk_bf16_f32 v112, v116, v117
	v_lshlrev_b32_e32 v116, 7, v152
	v_and_b32_e32 v136, 0x6780, v116
	v_pk_mul_f32 v[118:119], v[118:119], v[164:165]
	v_lshl_add_u64 v[116:117], s[20:21], 0, v[136:137]
	v_mov_b32_e32 v149, v137
	v_cvt_pk_bf16_f32 v113, v118, v119
	v_cvt_pk_bf16_f32 v114, v114, v115
	v_cvt_pk_bf16_f32 v115, v120, v121
	v_lshl_add_u64 v[116:117], v[116:117], 0, v[148:149]
	global_store_dwordx4 v[116:117], v[112:115], off
	s_nop 1
	v_mul_f32_e32 v112, 0xbfb8aa3b, v172
	v_pk_mul_f32 v[118:119], v[110:111], v[112:113] op_sel_hi:[1,0]
	v_pk_mul_f32 v[120:121], v[108:109], v[112:113] op_sel_hi:[1,0]
	v_pk_mul_f32 v[122:123], v[106:107], v[112:113] op_sel_hi:[1,0]
	v_pk_mul_f32 v[112:113], v[104:105], v[112:113] op_sel_hi:[1,0]
	v_exp_f32_e32 v120, v120
	v_exp_f32_e32 v121, v121
	v_exp_f32_e32 v118, v118
	v_exp_f32_e32 v119, v119
	v_exp_f32_e32 v112, v112
	v_exp_f32_e32 v122, v122
	v_exp_f32_e32 v123, v123
	v_exp_f32_e32 v113, v113
	v_pk_fma_f32 v[118:119], v[118:119], v[234:235], v[234:235]
	v_pk_fma_f32 v[120:121], v[120:121], v[234:235], v[234:235]
; __device__ __forceinline__ unsigned cvt_pk_bf16(float lo, float hi) { typedef float f2 __attribute__((ext_vector_type(2))); const bf16v2 r = __builtin_convertvector((f2){lo, hi}, bf16v2); return __builtin_bit_cast(unsigned, r); }
;     __device__ __forceinline__ void operator()(const f32x4 (&acc)[2][2][4][2], const Unit& u, int wr, int wc, int fr, int fq) const {
;     ...
;                 const int row = row0 + ai * HALF + m * 16; const float rs = rsv[ai][m], cexp = -1.4426950408889634f * rs, rs2 = rs * rs;
;                 const f32x4 g0 = acc[ai][0][m][0], g1 = acc[ai][0][m][1], u0 = acc[ai][1][m][0], u1 = acc[ai][1][m][1];
;                 const f32x4 t0 = g0 * cexp, t1 = g1 * cexp;
;                 f32x4 d0 = (f32x4){__builtin_amdgcn_exp2f(t0[0]), __builtin_amdgcn_exp2f(t0[1]), __builtin_amdgcn_exp2f(t0[2]), __builtin_amdgcn_exp2f(t0[3])} + 1.0f;
;                 f32x4 d1 = (f32x4){__builtin_amdgcn_exp2f(t1[0]), __builtin_amdgcn_exp2f(t1[1]), __builtin_amdgcn_exp2f(t1[2]), __builtin_amdgcn_exp2f(t1[3])} + 1.0f;
;                 const f32x4 r0 = (f32x4){__builtin_amdgcn_rcpf(d0[0]), __builtin_amdgcn_rcpf(d0[1]), __builtin_amdgcn_rcpf(d0[2]), __builtin_amdgcn_rcpf(d0[3])} * rs2;
;                 const f32x4 r1 = (f32x4){__builtin_amdgcn_rcpf(d1[0]), __builtin_amdgcn_rcpf(d1[1]), __builtin_amdgcn_rcpf(d1[2]), __builtin_amdgcn_rcpf(d1[3])} * rs2;
;                 const f32x4 a0 = (g0 * u0) * r0, a1 = (g1 * u1) * r1;
;                 u32x4 w; w.x = cvt_pk_bf16(a0[0], a0[1]); w.y = cvt_pk_bf16(a0[2], a0[3]); w.z = cvt_pk_bf16(a1[0], a1[1]); w.w = cvt_pk_bf16(a1[2], a1[3]);
;                 *(u32x4*)(O + (((size_t)(row >> 8) * (DFF / BK) + (col0 >> 6)) * BM + (row & 255)) * BK + (col0 & 63)) = w;
	v_pk_fma_f32 v[122:123], v[122:123], v[234:235], v[234:235]
	v_pk_fma_f32 v[112:113], v[112:113], v[234:235], v[234:235]
	v_rcp_f32_e32 v120, v120
	v_rcp_f32_e32 v121, v121
	v_rcp_f32_e32 v118, v118
	v_rcp_f32_e32 v119, v119
	v_rcp_f32_e32 v112, v112
	v_rcp_f32_e32 v113, v113
	v_rcp_f32_e32 v122, v122
	v_rcp_f32_e32 v123, v123
	s_nop 0
	v_pk_mul_f32 v[102:103], v[102:103], v[118:119]
	v_pk_mul_f32 v[100:101], v[100:101], v[120:121]
	v_pk_mul_f32 v[104:105], v[98:99], v[122:123]
	v_pk_mul_f32 v[98:99], v[96:97], v[112:113]
	v_cvt_pk_bf16_f32 v96, v100, v101
	v_cvt_pk_bf16_f32 v97, v102, v103
	v_cvt_pk_bf16_f32 v98, v98, v99
	v_cvt_pk_bf16_f32 v99, v104, v105
	global_store_dwordx4 v[116:117], v[96:99], off offset:2048
	s_nop 1
	v_mul_f32_e32 v96, 0xbfb8aa3b, v153
	v_pk_mul_f32 v[102:103], v[92:93], v[96:97] op_sel_hi:[1,0]
	v_pk_mul_f32 v[100:101], v[94:95], v[96:97] op_sel_hi:[1,0]
	v_pk_mul_f32 v[104:105], v[90:91], v[96:97] op_sel_hi:[1,0]
	v_pk_mul_f32 v[96:97], v[88:89], v[96:97] op_sel_hi:[1,0]
	v_exp_f32_e32 v102, v102
	v_exp_f32_e32 v103, v103
	v_exp_f32_e32 v100, v100
	v_exp_f32_e32 v101, v101
	v_exp_f32_e32 v96, v96
	v_exp_f32_e32 v104, v104
	v_exp_f32_e32 v105, v105
	v_exp_f32_e32 v97, v97
	v_pk_fma_f32 v[102:103], v[102:103], v[238:239], v[238:239]
	v_pk_fma_f32 v[100:101], v[100:101], v[238:239], v[238:239]
	v_pk_fma_f32 v[104:105], v[104:105], v[238:239], v[238:239]
	v_pk_fma_f32 v[96:97], v[96:97], v[238:239], v[238:239]
	v_rcp_f32_e32 v102, v102
	v_rcp_f32_e32 v103, v103
	v_rcp_f32_e32 v100, v100
	v_rcp_f32_e32 v101, v101
	v_rcp_f32_e32 v96, v96
	v_rcp_f32_e32 v97, v97
	v_rcp_f32_e32 v104, v104
	v_rcp_f32_e32 v105, v105
	s_nop 0
	v_pk_mul_f32 v[84:85], v[84:85], v[102:103]
	v_pk_mul_f32 v[86:87], v[86:87], v[100:101]
	v_pk_mul_f32 v[88:89], v[82:83], v[104:105]
	v_pk_mul_f32 v[82:83], v[80:81], v[96:97]
	v_cvt_pk_bf16_f32 v80, v84, v85
	v_add_co_u32_e32 v84, vcc, s62, v116
	v_cvt_pk_bf16_f32 v81, v86, v87
	v_cvt_pk_bf16_f32 v82, v82, v83
	v_cvt_pk_bf16_f32 v83, v88, v89
	v_addc_co_u32_e32 v85, vcc, 0, v117, vcc
	global_store_dwordx4 v[84:85], v[80:83], off
	s_nop 1
	v_mul_f32_e32 v80, 0xbfb8aa3b, v161
	v_pk_mul_f32 v[86:87], v[78:79], v[80:81] op_sel_hi:[1,0]
	v_pk_mul_f32 v[88:89], v[76:77], v[80:81] op_sel_hi:[1,0]
	v_pk_mul_f32 v[90:91], v[74:75], v[80:81] op_sel_hi:[1,0]
	v_pk_mul_f32 v[80:81], v[72:73], v[80:81] op_sel_hi:[1,0]
	v_exp_f32_e32 v88, v88
	v_exp_f32_e32 v89, v89
	v_exp_f32_e32 v86, v86
	v_exp_f32_e32 v87, v87
	v_exp_f32_e32 v80, v80
	v_exp_f32_e32 v90, v90
	v_exp_f32_e32 v91, v91
	v_exp_f32_e32 v81, v81
	v_pk_fma_f32 v[86:87], v[86:87], v[240:241], v[240:241]
	v_pk_fma_f32 v[88:89], v[88:89], v[240:241], v[240:241]
	v_pk_fma_f32 v[90:91], v[90:91], v[240:241], v[240:241]
	v_pk_fma_f32 v[80:81], v[80:81], v[240:241], v[240:241]
	v_rcp_f32_e32 v88, v88
	v_rcp_f32_e32 v89, v89
	v_rcp_f32_e32 v86, v86
	v_rcp_f32_e32 v87, v87
	v_rcp_f32_e32 v80, v80
	v_rcp_f32_e32 v81, v81
	v_rcp_f32_e32 v90, v90
	v_rcp_f32_e32 v91, v91
	s_nop 0
	v_pk_mul_f32 v[70:71], v[70:71], v[86:87]
	v_pk_mul_f32 v[68:69], v[68:69], v[88:89]
	v_pk_mul_f32 v[72:73], v[66:67], v[90:91]
	v_pk_mul_f32 v[66:67], v[64:65], v[80:81]
	v_cvt_pk_bf16_f32 v64, v68, v69
	v_cvt_pk_bf16_f32 v65, v70, v71
	v_cvt_pk_bf16_f32 v66, v66, v67
	v_cvt_pk_bf16_f32 v67, v72, v73
	global_store_dwordx4 v[84:85], v[64:67], off offset:2048
	s_nop 0
	v_mul_f32_e32 v66, 0xbfb8aa3b, v173
	v_pk_mul_f32 v[70:71], v[62:63], v[66:67] op_sel_hi:[1,0]
	v_pk_mul_f32 v[72:73], v[60:61], v[66:67] op_sel_hi:[1,0]
	v_pk_mul_f32 v[74:75], v[58:59], v[66:67] op_sel_hi:[1,0]
	v_pk_mul_f32 v[66:67], v[56:57], v[66:67] op_sel_hi:[1,0]
	v_exp_f32_e32 v70, v70
	v_exp_f32_e32 v71, v71
	v_exp_f32_e32 v72, v72
	v_exp_f32_e32 v73, v73
	v_exp_f32_e32 v66, v66
	v_exp_f32_e32 v74, v74
	v_exp_f32_e32 v75, v75
	v_exp_f32_e32 v67, v67
	v_pk_fma_f32 v[70:71], v[70:71], v[236:237], v[236:237]
	v_pk_fma_f32 v[72:73], v[72:73], v[236:237], v[236:237]
	v_pk_fma_f32 v[74:75], v[74:75], v[236:237], v[236:237]
	v_pk_fma_f32 v[66:67], v[66:67], v[236:237], v[236:237]
	v_rcp_f32_e32 v70, v70
	v_rcp_f32_e32 v71, v71
	v_rcp_f32_e32 v72, v72
	v_rcp_f32_e32 v73, v73
	v_rcp_f32_e32 v66, v66
	v_rcp_f32_e32 v67, v67
	v_rcp_f32_e32 v74, v74
	v_rcp_f32_e32 v75, v75
	v_lshrrev_b32_e32 v64, 8, v150
	v_mad_i32_i24 v64, v64, 44, s11
	v_ashrrev_i32_e32 v65, 31, v64
	s_nop 0
	v_pk_mul_f32 v[54:55], v[54:55], v[70:71]
	v_lshlrev_b64 v[64:65], 15, v[64:65]
	v_pk_mul_f32 v[52:53], v[52:53], v[72:73]
; #define PG8_BAR __builtin_amdgcn_s_barrier()
;     __device__ __forceinline__ void operator()(const f32x4 (&acc)[2][2][4][2], const Unit& u, int wr, int wc, int fr, int fq) const {
;     ...
;                 const int row = row0 + ai * HALF + m * 16; const float rs = rsv[ai][m], cexp = -1.4426950408889634f * rs, rs2 = rs * rs;
;                 const f32x4 g0 = acc[ai][0][m][0], g1 = acc[ai][0][m][1], u0 = acc[ai][1][m][0], u1 = acc[ai][1][m][1];
;                 const f32x4 t0 = g0 * cexp, t1 = g1 * cexp;
;                 f32x4 d0 = (f32x4){__builtin_amdgcn_exp2f(t0[0]), __builtin_amdgcn_exp2f(t0[1]), __builtin_amdgcn_exp2f(t0[2]), __builtin_amdgcn_exp2f(t0[3])} + 1.0f;
;                 f32x4 d1 = (f32x4){__builtin_amdgcn_exp2f(t1[0]), __builtin_amdgcn_exp2f(t1[1]), __builtin_amdgcn_exp2f(t1[2]), __builtin_amdgcn_exp2f(t1[3])} + 1.0f;
;                 const f32x4 r0 = (f32x4){__builtin_amdgcn_rcpf(d0[0]), __builtin_amdgcn_rcpf(d0[1]), __builtin_amdgcn_rcpf(d0[2]), __builtin_amdgcn_rcpf(d0[3])} * rs2;
;                 const f32x4 r1 = (f32x4){__builtin_amdgcn_rcpf(d1[0]), __builtin_amdgcn_rcpf(d1[1]), __builtin_amdgcn_rcpf(d1[2]), __builtin_amdgcn_rcpf(d1[3])} * rs2;
;                 const f32x4 a0 = (g0 * u0) * r0, a1 = (g1 * u1) * r1;
;                 u32x4 w; w.x = cvt_pk_bf16(a0[0], a0[1]); w.y = cvt_pk_bf16(a0[2], a0[3]); w.z = cvt_pk_bf16(a1[0], a1[1]); w.w = cvt_pk_bf16(a1[2], a1[3]);
;                 *(u32x4*)(O + (((size_t)(row >> 8) * (DFF / BK) + (col0 >> 6)) * BM + (row & 255)) * BK + (col0 & 63)) = w;
; template <class Epi, class Sched, bool ALIGN_EPI = false, bool SP2 = false, bool ATILED = false>
; __device__ __forceinline__ void gemm_phase(PG8_LAS unsigned char* lds, const Gemm g, const Sched& S, const Epi& E) {
;     ...
;         if constexpr (ALIGN_EPI) { if (wr == 0) PG8_BAR; }
;         if constexpr (!Epi::AFTER_DRAIN) { E(acc, cur, wr, wc, fr, fq); S.done(cur); }
;         if (!has_next) break;
; #pragma unroll
;         for (int a = 0; a < 2; ++a)
; #pragma unroll
;             for (int b = 0; b < 2; ++b)
; #pragma unroll
;                 for (int m = 0; m < 4; ++m)
; #pragma unroll
;                     for (int n = 0; n < 2; ++n) acc[a][b][m][n] = (f32x4){0.f, 0.f, 0.f, 0.f};
;         cur = nxt; cA = nA; cB = nB; ++ui;
;         if constexpr (ALIGN_EPI) { if (wr == 1) PG8_BAR; }
	v_pk_mul_f32 v[56:57], v[50:51], v[74:75]
	v_pk_mul_f32 v[50:51], v[48:49], v[66:67]
	v_cvt_pk_bf16_f32 v49, v54, v55
	v_lshlrev_b32_e32 v54, 7, v150
	v_cvt_pk_bf16_f32 v48, v52, v53
	v_lshl_add_u64 v[52:53], s[36:37], 0, v[64:65]
	v_and_b32_e32 v136, 0x6780, v54
	v_lshl_add_u64 v[52:53], v[52:53], 0, v[136:137]
	v_cvt_pk_bf16_f32 v50, v50, v51
	v_cvt_pk_bf16_f32 v51, v56, v57
	v_lshl_add_u64 v[52:53], v[52:53], 0, v[148:149]
	global_store_dwordx4 v[52:53], v[48:51], off
	s_nop 1
	v_mul_f32_e32 v48, 0xbfb8aa3b, v174
	v_pk_mul_f32 v[54:55], v[46:47], v[48:49] op_sel_hi:[1,0]
	v_pk_mul_f32 v[56:57], v[44:45], v[48:49] op_sel_hi:[1,0]
	v_pk_mul_f32 v[58:59], v[42:43], v[48:49] op_sel_hi:[1,0]
	v_pk_mul_f32 v[48:49], v[40:41], v[48:49] op_sel_hi:[1,0]
	v_exp_f32_e32 v56, v56
	v_exp_f32_e32 v57, v57
	v_exp_f32_e32 v54, v54
	v_exp_f32_e32 v55, v55
	v_exp_f32_e32 v48, v48
	v_exp_f32_e32 v58, v58
	v_exp_f32_e32 v59, v59
	v_exp_f32_e32 v49, v49
	v_pk_fma_f32 v[54:55], v[54:55], v[242:243], v[242:243]
	v_pk_fma_f32 v[56:57], v[56:57], v[242:243], v[242:243]
	v_pk_fma_f32 v[58:59], v[58:59], v[242:243], v[242:243]
	v_pk_fma_f32 v[48:49], v[48:49], v[242:243], v[242:243]
	v_rcp_f32_e32 v56, v56
	v_rcp_f32_e32 v57, v57
	v_rcp_f32_e32 v54, v54
	v_rcp_f32_e32 v55, v55
	v_rcp_f32_e32 v48, v48
	v_rcp_f32_e32 v49, v49
	v_rcp_f32_e32 v58, v58
	v_rcp_f32_e32 v59, v59
	s_nop 0
	v_pk_mul_f32 v[38:39], v[38:39], v[54:55]
	v_pk_mul_f32 v[36:37], v[36:37], v[56:57]
	v_pk_mul_f32 v[40:41], v[34:35], v[58:59]
	v_pk_mul_f32 v[34:35], v[32:33], v[48:49]
	v_cvt_pk_bf16_f32 v32, v36, v37
	v_cvt_pk_bf16_f32 v33, v38, v39
	v_cvt_pk_bf16_f32 v34, v34, v35
	v_cvt_pk_bf16_f32 v35, v40, v41
	global_store_dwordx4 v[52:53], v[32:35], off offset:2048
	s_nop 1
	v_mul_f32_e32 v32, 0xbfb8aa3b, v175
	v_pk_mul_f32 v[38:39], v[28:29], v[32:33] op_sel_hi:[1,0]
	v_pk_mul_f32 v[36:37], v[30:31], v[32:33] op_sel_hi:[1,0]
	v_pk_mul_f32 v[40:41], v[26:27], v[32:33] op_sel_hi:[1,0]
	v_pk_mul_f32 v[32:33], v[24:25], v[32:33] op_sel_hi:[1,0]
	v_exp_f32_e32 v38, v38
	v_exp_f32_e32 v39, v39
	v_exp_f32_e32 v36, v36
	v_exp_f32_e32 v37, v37
	v_exp_f32_e32 v32, v32
	v_exp_f32_e32 v40, v40
	v_exp_f32_e32 v41, v41
	v_exp_f32_e32 v33, v33
	v_pk_fma_f32 v[38:39], v[38:39], v[244:245], v[244:245]
	v_pk_fma_f32 v[36:37], v[36:37], v[244:245], v[244:245]
	v_pk_fma_f32 v[40:41], v[40:41], v[244:245], v[244:245]
	v_pk_fma_f32 v[32:33], v[32:33], v[244:245], v[244:245]
	v_rcp_f32_e32 v38, v38
	v_rcp_f32_e32 v39, v39
	v_rcp_f32_e32 v36, v36
	v_rcp_f32_e32 v37, v37
	v_rcp_f32_e32 v32, v32
	v_rcp_f32_e32 v33, v33
	v_rcp_f32_e32 v40, v40
	v_rcp_f32_e32 v41, v41
	s_nop 0
	v_pk_mul_f32 v[20:21], v[20:21], v[38:39]
	v_pk_mul_f32 v[22:23], v[22:23], v[36:37]
	v_pk_mul_f32 v[24:25], v[18:19], v[40:41]
	v_pk_mul_f32 v[18:19], v[16:17], v[32:33]
	v_cvt_pk_bf16_f32 v16, v20, v21
	v_add_co_u32_e32 v20, vcc, s62, v52
	v_cvt_pk_bf16_f32 v17, v22, v23
	v_cvt_pk_bf16_f32 v18, v18, v19
	v_cvt_pk_bf16_f32 v19, v24, v25
	v_addc_co_u32_e32 v21, vcc, 0, v53, vcc
	global_store_dwordx4 v[20:21], v[16:19], off
	s_andn2_b64 vcc, exec, s[0:1]
	s_mov_b64 s[0:1], -1
	v_mul_f32_e32 v16, 0xbfb8aa3b, v151
	v_pk_mul_f32 v[22:23], v[14:15], v[16:17] op_sel_hi:[1,0]
	v_pk_mul_f32 v[24:25], v[12:13], v[16:17] op_sel_hi:[1,0]
	v_pk_mul_f32 v[26:27], v[10:11], v[16:17] op_sel_hi:[1,0]
	v_pk_mul_f32 v[16:17], v[8:9], v[16:17] op_sel_hi:[1,0]
	v_exp_f32_e32 v24, v24
	v_exp_f32_e32 v25, v25
	v_exp_f32_e32 v22, v22
	v_exp_f32_e32 v23, v23
	v_exp_f32_e32 v16, v16
	v_exp_f32_e32 v26, v26
	v_exp_f32_e32 v27, v27
	v_exp_f32_e32 v17, v17
	v_pk_fma_f32 v[22:23], v[22:23], v[246:247], v[246:247]
	v_pk_fma_f32 v[24:25], v[24:25], v[246:247], v[246:247]
	v_pk_fma_f32 v[26:27], v[26:27], v[246:247], v[246:247]
	v_pk_fma_f32 v[16:17], v[16:17], v[246:247], v[246:247]
	v_rcp_f32_e32 v24, v24
	v_rcp_f32_e32 v25, v25
	v_rcp_f32_e32 v22, v22
	v_rcp_f32_e32 v23, v23
	v_rcp_f32_e32 v16, v16
	v_rcp_f32_e32 v17, v17
	v_rcp_f32_e32 v26, v26
	v_rcp_f32_e32 v27, v27
	s_nop 0
	v_pk_mul_f32 v[6:7], v[6:7], v[22:23]
	v_pk_mul_f32 v[4:5], v[4:5], v[24:25]
	v_pk_mul_f32 v[8:9], v[2:3], v[26:27]
	v_pk_mul_f32 v[2:3], v[0:1], v[16:17]
	v_cvt_pk_bf16_f32 v0, v4, v5
	v_cvt_pk_bf16_f32 v1, v6, v7
	v_cvt_pk_bf16_f32 v2, v2, v3
	v_cvt_pk_bf16_f32 v3, v8, v9
	global_store_dwordx4 v[20:21], v[0:3], off offset:2048
	s_cbranch_vccnz .LBB0_813
	s_andn2_b64 vcc, exec, s[4:5]
	s_cbranch_vccnz .LBB0_812
	s_barrier
	s_branch .LBB0_812
